# SB attention tile loop: 15 v_max(x,x) canonicalisations folded into the following v_max(0,x)
# speedup vs baseline: 1.0032x; 1.0032x over previous
; #define LAS __attribute__((address_space(3)))
; __device__ __forceinline__ int crow(int r, int hi) { return (r & 3) + 8 * (r >> 2) + 4 * hi; }
; __device__ __forceinline__ float softplus2(float y) { return fmaxf(y, 0.f) + lg2(1.0f + ex2(-fabsf(y))); }
; #define MFMA32(a, b, c) __builtin_amdgcn_mfma_f32_32x32x16_bf16((a), (b), (c), 0, 0, 0)
; template <bool MASK> __device__ __forceinline__ void sb_tile(f32x16& p0, f32x16& p1, float& carry, int kv0, int qpos, int hi) {
;     ...
;     for (int r = 0; r < 16; ++r) { float s0 = softplus2(p0[r]), s1 = softplus2(p1[r]);
;         if (MASK) { if (kv0 + crow(r, hi) >= qpos) s0 = 0.f; if (kv0 + 32 + crow(r, hi) >= qpos) s1 = 0.f; }
;         sp0[r] = s0; sp1[r] = s1; }
; __device__ __forceinline__ void attn_unit_sb(int b, int h, int qb, const bf16_t* __restrict__ Q, const bf16_t* __restrict__ K, const bf16_t* __restrict__ Vt, bf16_t* __restrict__ O, LAS unsigned char* lds) {
;     ...
;             for (int d0 = 0; d0 < ND; ++d0) { const bf16x8 a0 = *(const LAS bf16x8*)(kb + d0 * 32), a1 = *(const LAS bf16x8*)(kb + 32 * KP + d0 * 32);
;                 p0 = MFMA32(a0, qr[d0], p0); p1 = MFMA32(a1, qr[d0], p1); }
;             sb_tile<true>(p0, p1, carry, jt * 64, qpos, hi);
.LBB0_489:
	v_add_u32_e32 v14, 0, v198
	ds_read_b128 v[2:5], v14 offset:4608
	ds_read_b128 v[6:9], v14
	ds_read_b128 v[10:13], v14 offset:32
	s_add_i32 s5, s19, 32
	v_or_b32_e32 v197, s19, v101
	s_waitcnt lgkmcnt(2)
	v_mfma_f32_32x32x16_bf16 v[64:79], v[2:5], v[84:87], 0
	ds_read_b128 v[2:5], v14 offset:4640
	v_or_b32_e32 v199, s5, v108
	v_cmp_lt_i32_e64 s[58:59], v199, v104
	v_cmp_lt_i32_e64 s[6:7], v197, v105
	v_or_b32_e32 v197, s19, v109
	v_or_b32_e32 v199, s5, v110
	v_cmp_lt_i32_e64 s[60:61], v199, v104
	s_waitcnt lgkmcnt(2)
	v_mfma_f32_32x32x16_bf16 v[48:63], v[6:9], v[84:87], 0
	v_cmp_lt_i32_e64 s[44:45], v197, v105
	v_or_b32_e32 v197, s19, v111
	v_or_b32_e32 v199, s5, v112
	v_cmp_lt_i32_e64 s[62:63], v199, v104
	v_cmp_lt_i32_e64 s[46:47], v197, v105
	v_or_b32_e32 v197, s19, v113
	v_or_b32_e32 v199, s5, v114
	s_waitcnt lgkmcnt(1)
	v_mfma_f32_32x32x16_bf16 v[48:63], v[10:13], v[88:91], v[48:63]
	v_cmp_lt_i32_e64 s[64:65], v199, v104
	v_cmp_lt_i32_e64 s[48:49], v197, v105
	v_or_b32_e32 v197, s19, v115
	v_or_b32_e32 v199, s5, v116
	v_cmp_lt_i32_e64 s[66:67], v199, v104
	v_cmp_lt_i32_e64 s[50:51], v197, v105
	v_or_b32_e32 v197, s19, v117
	s_waitcnt lgkmcnt(0)
	v_mfma_f32_32x32x16_bf16 v[64:79], v[2:5], v[88:91], v[64:79]
	ds_read_b128 v[2:5], v14 offset:64
	ds_read_b128 v[6:9], v14 offset:4672
	v_or_b32_e32 v199, s5, v118
	v_cmp_lt_i32_e64 s[68:69], v199, v104
	v_cmp_lt_i32_e64 s[52:53], v197, v105
	v_or_b32_e32 v197, s19, v119
	v_or_b32_e32 v199, s5, v120
	v_cmp_lt_i32_e64 s[70:71], v199, v104
	s_waitcnt lgkmcnt(1)
	v_mfma_f32_32x32x16_bf16 v[48:63], v[2:5], v[92:95], v[48:63]
	v_cmp_lt_i32_e64 s[54:55], v197, v105
	v_or_b32_e32 v197, s19, v121
	v_or_b32_e32 v199, s5, v122
	v_cmp_lt_i32_e64 s[72:73], v199, v104
	v_cmp_lt_i32_e64 s[56:57], v197, v105
	v_or_b32_e32 v197, s19, v123
	v_or_b32_e32 v199, s5, v124
	s_waitcnt lgkmcnt(0)
	v_mfma_f32_32x32x16_bf16 v[64:79], v[6:9], v[92:95], v[64:79]
	ds_read_b128 v[2:5], v14 offset:96
	ds_read_b128 v[6:9], v14 offset:4704
	v_cmp_lt_i32_e64 s[74:75], v199, v104
	v_cmp_lt_i32_e64 s[76:77], v197, v105
	v_or_b32_e32 v197, s19, v125
	v_or_b32_e32 v199, s5, v126
	v_cmp_lt_i32_e64 s[78:79], v199, v104
	v_cmp_lt_i32_e64 s[80:81], v197, v105
	s_waitcnt lgkmcnt(1)
	v_mfma_f32_32x32x16_bf16 v[48:63], v[2:5], v[96:99], v[48:63]
	v_or_b32_e32 v197, s19, v127
	v_or_b32_e32 v199, s5, v128
	v_cmp_lt_i32_e64 s[82:83], v199, v104
	v_cmp_lt_i32_e64 s[84:85], v197, v105
	v_or_b32_e32 v197, s19, v129
	v_or_b32_e32 v199, s5, v130
	v_cmp_lt_i32_e64 s[86:87], v199, v104
	s_waitcnt lgkmcnt(0)
	v_mfma_f32_32x32x16_bf16 v[64:79], v[6:9], v[96:99], v[64:79]
	s_nop 2
	v_exp_f32_e64 v5, -|v49|
	v_exp_f32_e64 v2, -|v48|
	v_max_f32_e32 v9, v49, v49
	v_max_f32_e32 v9, 0, v9
	v_add_f32_e32 v5, 1.0, v5
	v_log_f32_e32 v7, v5
	v_add_f32_e32 v2, 1.0, v2
	s_nop 1
	v_max_f32_e32 v5, v65, v65
	v_max_f32_e32 v8, 0, v5
	v_exp_f32_e64 v5, -|v65|
	v_log_f32_e32 v3, v2
	v_max_f32_e32 v2, v64, v64
	v_max_f32_e32 v4, 0, v2
	v_add_f32_e32 v5, 1.0, v5
	v_log_f32_e32 v6, v5
	v_exp_f32_e64 v5, -|v50|
	v_exp_f32_e64 v2, -|v64|
	v_max_f32_e32 v13, v50, v50
	v_max_f32_e32 v13, 0, v13
	v_add_f32_e32 v5, 1.0, v5
	v_log_f32_e32 v11, v5
	v_max_f32_e32 v12, 0, v66
	v_exp_f32_e64 v5, -|v66|
	v_add_f32_e32 v2, 1.0, v2
	v_log_f32_e32 v2, v2
	v_max_f32_e32 v141, v51, v51
	v_add_f32_e32 v5, 1.0, v5
	v_log_f32_e32 v10, v5
	v_exp_f32_e64 v5, -|v51|
	v_max_f32_e32 v141, 0, v141
	v_max_f32_e32 v145, v52, v52
	v_max_f32_e32 v161, v56, v56
	v_add_f32_e32 v5, 1.0, v5
	v_log_f32_e32 v15, v5
	v_max_f32_e32 v140, 0, v67
	v_exp_f32_e64 v5, -|v67|
	v_max_f32_e32 v145, 0, v145
	v_max_f32_e32 v149, v53, v53
	v_max_f32_e32 v161, 0, v161
	v_add_f32_e32 v5, 1.0, v5
	v_log_f32_e32 v14, v5
	v_exp_f32_e64 v5, -|v52|
	v_max_f32_e32 v165, v57, v57
	v_max_f32_e32 v149, 0, v149
	v_max_f32_e32 v165, 0, v165
	v_add_f32_e32 v5, 1.0, v5
	v_log_f32_e32 v143, v5
	v_max_f32_e32 v144, 0, v68
	v_exp_f32_e64 v5, -|v68|
	v_max_f32_e32 v169, v58, v58
	v_max_f32_e32 v153, v54, v54
	v_max_f32_e32 v169, 0, v169
	v_add_f32_e32 v5, 1.0, v5
	v_log_f32_e32 v142, v5
	v_exp_f32_e64 v5, -|v53|
	v_max_f32_e32 v173, v59, v59
	v_max_f32_e32 v153, 0, v153
	v_max_f32_e32 v173, 0, v173
	v_add_f32_e32 v5, 1.0, v5
	v_log_f32_e32 v147, v5
	v_max_f32_e32 v148, 0, v69
	v_exp_f32_e64 v5, -|v69|
	v_max_f32_e32 v177, v60, v60
	v_max_f32_e32 v157, v55, v55
	v_max_f32_e32 v177, 0, v177
	v_add_f32_e32 v5, 1.0, v5
	v_log_f32_e32 v146, v5
	v_exp_f32_e64 v5, -|v54|
	v_max_f32_e32 v181, v61, v61
	v_cmp_lt_i32_e64 s[88:89], v197, v105
	v_or_b32_e32 v197, s19, v131
	v_add_f32_e32 v5, 1.0, v5
	v_log_f32_e32 v151, v5
	v_max_f32_e32 v152, 0, v70
	v_exp_f32_e64 v5, -|v70|
	v_or_b32_e32 v199, s5, v132
	v_max_f32_e32 v157, 0, v157
	v_max_f32_e32 v181, 0, v181
	v_add_f32_e32 v5, 1.0, v5
	v_log_f32_e32 v150, v5
	v_exp_f32_e64 v5, -|v55|
	v_max_f32_e32 v185, v62, v62
	v_cmp_lt_i32_e64 s[90:91], v199, v104
	v_cmp_lt_i32_e64 s[92:93], v197, v105
	v_add_f32_e32 v5, 1.0, v5
	v_log_f32_e32 v155, v5
	v_max_f32_e32 v156, 0, v71
	v_exp_f32_e64 v5, -|v71|
	v_or_b32_e32 v197, s19, v133
	v_or_b32_e32 v199, s5, v134
	v_max_f32_e32 v185, 0, v185
	v_add_f32_e32 v5, 1.0, v5
	v_log_f32_e32 v154, v5
	v_exp_f32_e64 v5, -|v56|
	v_max_f32_e32 v189, v63, v63
	v_cmp_lt_i32_e64 s[94:95], v199, v104
	v_cmp_lt_i32_e64 s[96:97], v197, v105
	v_add_f32_e32 v5, 1.0, v5
	v_log_f32_e32 v159, v5
	v_max_f32_e32 v160, 0, v72
	v_exp_f32_e64 v5, -|v72|
	v_or_b32_e32 v197, s19, v135
	v_or_b32_e32 v199, s5, v136
	s_mov_b32 s4, s10
	v_add_f32_e32 v5, 1.0, v5
	v_log_f32_e32 v158, v5
	v_exp_f32_e64 v5, -|v57|
	v_max_f32_e32 v189, 0, v189
	v_cmp_lt_i32_e64 s[8:9], v199, v104
; __device__ __forceinline__ int crow(int r, int hi) { return (r & 3) + 8 * (r >> 2) + 4 * hi; }
; __device__ __forceinline__ float softplus2(float y) { return fmaxf(y, 0.f) + lg2(1.0f + ex2(-fabsf(y))); }
; template <bool MASK> __device__ __forceinline__ void sb_tile(f32x16& p0, f32x16& p1, float& carry, int kv0, int qpos, int hi) {
;     ...
;     for (int r = 0; r < 16; ++r) { float s0 = softplus2(p0[r]), s1 = softplus2(p1[r]);
;         if (MASK) { if (kv0 + crow(r, hi) >= qpos) s0 = 0.f; if (kv0 + 32 + crow(r, hi) >= qpos) s1 = 0.f; }
;         sp0[r] = s0; sp1[r] = s1; }
;     float tl0[4], tl1[4], bt0, bt1;
;     { float G[4], Go[4], T[4];
; #pragma unroll
;       for (int i = 0; i < 4; ++i) { sp1[4 * i + 2] += sp1[4 * i + 3]; sp1[4 * i + 1] += sp1[4 * i + 2]; sp1[4 * i] += sp1[4 * i + 1]; G[i] = sp1[4 * i]; }
; #pragma unroll
;       for (int i = 0; i < 4; ++i) { Go[i] = xhalf(G[i], hi); T[i] = G[i] + Go[i]; }
;       const float st2 = T[3], st1 = T[3] + T[2], st0 = st1 + T[1]; bt1 = st0 + T[0];
;       tl1[3] = carry + (hi ? 0.f : Go[3]); tl1[2] = carry + st2 + (hi ? 0.f : Go[2]); tl1[1] = carry + st1 + (hi ? 0.f : Go[1]); tl1[0] = carry + st0 + (hi ? 0.f : Go[0]); }
	v_cmp_lt_i32_e64 s[10:11], v197, v105
	v_add_f32_e32 v5, 1.0, v5
	v_log_f32_e32 v163, v5
	v_max_f32_e32 v164, 0, v73
	v_exp_f32_e64 v5, -|v73|
	v_or_b32_e32 v197, s19, v137
	v_or_b32_e32 v199, s5, v138
	v_cmp_lt_i32_e64 s[12:13], v199, v104
	v_add_f32_e32 v5, 1.0, v5
	v_log_f32_e32 v162, v5
	v_exp_f32_e64 v5, -|v58|
	v_cmp_lt_i32_e32 vcc, v197, v105
	s_mov_b32 s5, 0x43200000
	v_add_u32_e32 v198, 0xffffdc00, v198
	v_add_f32_e32 v5, 1.0, v5
	v_log_f32_e32 v167, v5
	v_max_f32_e32 v168, 0, v74
	v_exp_f32_e64 v5, -|v74|
	s_nop 0
	v_add_f32_e32 v5, 1.0, v5
	v_log_f32_e32 v166, v5
	v_exp_f32_e64 v5, -|v59|
	s_nop 0
	v_add_f32_e32 v5, 1.0, v5
	v_log_f32_e32 v171, v5
	v_max_f32_e32 v172, 0, v75
	v_exp_f32_e64 v5, -|v75|
	s_nop 0
	v_add_f32_e32 v5, 1.0, v5
	v_log_f32_e32 v170, v5
	v_exp_f32_e64 v5, -|v60|
	s_nop 0
	v_add_f32_e32 v5, 1.0, v5
	v_log_f32_e32 v175, v5
	v_max_f32_e32 v176, 0, v76
	v_exp_f32_e64 v5, -|v76|
	s_nop 0
	v_add_f32_e32 v5, 1.0, v5
	v_log_f32_e32 v174, v5
	v_exp_f32_e64 v5, -|v61|
	s_nop 0
	v_add_f32_e32 v5, 1.0, v5
	v_log_f32_e32 v179, v5
	v_max_f32_e32 v180, 0, v77
	v_exp_f32_e64 v5, -|v77|
	s_nop 0
	v_add_f32_e32 v5, 1.0, v5
	v_log_f32_e32 v178, v5
	v_exp_f32_e64 v5, -|v62|
	s_nop 0
	v_add_f32_e32 v5, 1.0, v5
	v_log_f32_e32 v183, v5
	v_max_f32_e32 v184, 0, v78
	v_exp_f32_e64 v5, -|v78|
	s_nop 0
	v_add_f32_e32 v5, 1.0, v5
	v_log_f32_e32 v182, v5
	v_exp_f32_e64 v5, -|v63|
	s_nop 0
	v_add_f32_e32 v5, 1.0, v5
	v_log_f32_e32 v187, v5
	v_max_f32_e32 v188, 0, v79
	v_exp_f32_e64 v5, -|v79|
	s_nop 0
	v_add_f32_e32 v5, 1.0, v5
	v_log_f32_e32 v186, v5
	v_max_f32_e32 v5, 0, v48
	v_pk_add_f32 v[2:3], v[4:5], v[2:3]
	s_nop 0
	v_cndmask_b32_e64 v201, 0, v3, s[6:7]
	v_cndmask_b32_e64 v200, 0, v2, s[58:59]
	v_pk_add_f32 v[2:3], v[8:9], v[6:7]
	s_nop 0
	v_cndmask_b32_e64 v7, 0, v3, s[44:45]
	v_cndmask_b32_e64 v6, 0, v2, s[60:61]
	v_pk_add_f32 v[2:3], v[12:13], v[10:11]
	v_pk_add_f32 v[12:13], v[160:161], v[158:159]
	v_cndmask_b32_e64 v9, 0, v3, s[46:47]
	v_cndmask_b32_e64 v8, 0, v2, s[62:63]
	v_pk_add_f32 v[2:3], v[140:141], v[14:15]
	s_nop 0
	v_cndmask_b32_e64 v5, 0, v3, s[48:49]
	v_cndmask_b32_e64 v4, 0, v2, s[64:65]
	v_pk_add_f32 v[2:3], v[144:145], v[142:143]
	s_nop 0
	v_cndmask_b32_e64 v11, 0, v3, s[50:51]
	v_cndmask_b32_e64 v10, 0, v2, s[66:67]
	v_pk_add_f32 v[2:3], v[148:149], v[146:147]
	v_cndmask_b32_e64 v147, 0, v13, s[76:77]
	v_cndmask_b32_e64 v146, 0, v12, s[74:75]
	v_pk_add_f32 v[12:13], v[164:165], v[162:163]
	v_cndmask_b32_e64 v143, 0, v3, s[52:53]
	v_cndmask_b32_e64 v149, 0, v13, s[80:81]
	v_cndmask_b32_e64 v148, 0, v12, s[78:79]
	v_pk_add_f32 v[12:13], v[168:169], v[166:167]
	v_cndmask_b32_e64 v142, 0, v2, s[68:69]
	v_pk_add_f32 v[2:3], v[152:153], v[150:151]
	v_cndmask_b32_e64 v151, 0, v13, s[84:85]
	v_cndmask_b32_e64 v150, 0, v12, s[82:83]
	v_pk_add_f32 v[12:13], v[172:173], v[170:171]
	v_cndmask_b32_e64 v145, 0, v3, s[54:55]
	v_cndmask_b32_e64 v153, 0, v13, s[88:89]
	v_cndmask_b32_e64 v152, 0, v12, s[86:87]
	v_pk_add_f32 v[12:13], v[176:177], v[174:175]
	v_cndmask_b32_e64 v144, 0, v2, s[70:71]
	v_pk_add_f32 v[2:3], v[156:157], v[154:155]
	v_cndmask_b32_e64 v155, 0, v13, s[92:93]
	v_cndmask_b32_e64 v154, 0, v12, s[90:91]
	v_pk_add_f32 v[12:13], v[180:181], v[178:179]
	v_pk_add_f32 v[150:151], v[150:151], v[152:153]
	v_cndmask_b32_e64 v157, 0, v13, s[96:97]
	v_cndmask_b32_e64 v156, 0, v12, s[94:95]
	v_pk_add_f32 v[12:13], v[184:185], v[182:183]
	v_cndmask_b32_e64 v3, 0, v3, s[56:57]
	v_cndmask_b32_e64 v159, 0, v13, s[10:11]
	v_cndmask_b32_e64 v158, 0, v12, s[8:9]
	v_pk_add_f32 v[12:13], v[188:189], v[186:187]
	v_cndmask_b32_e64 v2, 0, v2, s[72:73]
	v_cndmask_b32_e32 v161, 0, v13, vcc
	v_cndmask_b32_e64 v160, 0, v12, s[12:13]
	v_pk_add_f32 v[158:159], v[158:159], v[160:161]
	v_pk_add_f32 v[12:13], v[8:9], v[4:5]
	v_pk_add_f32 v[156:157], v[156:157], v[158:159]
	v_pk_add_f32 v[162:163], v[148:149], v[150:151]
	v_pk_add_f32 v[154:155], v[154:155], v[156:157]
	v_pk_add_f32 v[14:15], v[6:7], v[12:13]
	v_pk_add_f32 v[6:7], v[144:145], v[2:3]
	v_pk_add_f32 v[164:165], v[146:147], v[162:163]
	v_mov_b32_e32 v145, v154
	v_mov_b32_e32 v146, v154
	v_mov_b32_e32 v147, v155
	v_mov_b32_e32 v148, v155
	v_pk_add_f32 v[8:9], v[142:143], v[6:7]
	v_mov_b32_e32 v142, v164
	v_mov_b32_e32 v143, v164
	v_permlane32_swap_b32_e32 v145, v146
	v_permlane32_swap_b32_e32 v147, v148
	v_permlane32_swap_b32_e32 v142, v143
	v_cndmask_b32_e64 v167, v147, v148, s[40:41]
	v_cndmask_b32_e64 v166, v145, v146, s[40:41]
	v_mov_b32_e32 v146, v165
	v_mov_b32_e32 v147, v165
	v_pk_add_f32 v[10:11], v[10:11], v[8:9]
	v_cndmask_b32_e64 v145, 0, v166, s[40:41]
	v_pk_add_f32 v[168:169], v[154:155], v[166:167]
	v_permlane32_swap_b32_e32 v146, v147
	v_cndmask_b32_e64 v170, v142, v143, s[40:41]
	v_mov_b32_e32 v144, v10
	v_mov_b32_e32 v174, v10
	v_add_f32_e32 v175, v195, v145
	v_add_f32_e32 v145, v195, v168
	v_cndmask_b32_e64 v171, v146, v147, s[40:41]
	v_cndmask_b32_e64 v142, 0, v170, s[40:41]
	v_permlane32_swap_b32_e32 v144, v174
	v_add_f32_e32 v166, v142, v145
	v_pk_add_f32 v[142:143], v[164:165], v[170:171]
	v_mov_b32_e32 v145, v11
	v_mov_b32_e32 v147, v11
	v_pk_add_f32 v[142:143], v[142:143], v[168:169]
	s_nop 0
	v_permlane32_swap_b32_e32 v145, v147
	v_cndmask_b32_e64 v144, v144, v174, s[40:41]
	v_pk_add_f32 v[140:141], v[200:201], v[14:15]
	v_add_f32_e32 v146, v195, v142
	v_cndmask_b32_e64 v145, v145, v147, s[40:41]
	v_cndmask_b32_e64 v147, 0, v144, s[40:41]
	v_mov_b32_e32 v172, v140
	v_mov_b32_e32 v173, v140
	v_add_f32_e32 v168, v147, v146
	v_pk_add_f32 v[146:147], v[10:11], v[144:145]
	v_mov_b32_e32 v144, v141
	v_mov_b32_e32 v148, v141
	v_permlane32_swap_b32_e32 v172, v173
; #define LAS __attribute__((address_space(3)))
; __device__ __forceinline__ unsigned pk2(float lo, float hi) { f32x2_t v = {lo, hi}; bf16x2_t b = __builtin_convertvector(v, bf16x2_t); return __builtin_bit_cast(unsigned, b); }
; template <bool MASK> __device__ __forceinline__ void sb_tile(f32x16& p0, f32x16& p1, float& carry, int kv0, int qpos, int hi) {
;     ...
;       const float st2 = T[3], st1 = T[3] + T[2], st0 = st1 + T[1]; bt0 = st0 + T[0];
;       tl0[3] = base + (hi ? 0.f : Go[3]); tl0[2] = base + st2 + (hi ? 0.f : Go[2]); tl0[1] = base + st1 + (hi ? 0.f : Go[1]); tl0[0] = base + st0 + (hi ? 0.f : Go[0]); }
;     carry += bt0 + bt1;
; #pragma unroll
;     for (int r = 0; r < 16; ++r) { float w0 = ex2(p0[r] - (sp0[r] + tl0[r >> 2])), w1 = ex2(p1[r] - (sp1[r] + tl1[r >> 2]));
;         if (MASK) { if (kv0 + crow(r, hi) >= qpos) w0 = 0.f; if (kv0 + 32 + crow(r, hi) >= qpos) w1 = 0.f; }
;         p0[r] = w0; p1[r] = w1; }
; __device__ __forceinline__ void attn_unit_sb(int b, int h, int qb, const bf16_t* __restrict__ Q, const bf16_t* __restrict__ K, const bf16_t* __restrict__ Vt, bf16_t* __restrict__ O, LAS unsigned char* lds) {
;     ...
;             const LAS unsigned char* vb = lds + OFF_V + s * VBUF + q32 * VP + hi * 8;
; #pragma unroll
;             for (int j = 0; j < 4; ++j) {
;                 u32x4 pw;
;                 if (j < 2) { const int r0 = 8 * (j & 1); pw.x = pk2(p0[r0], p0[r0 + 1]); pw.y = pk2(p0[r0 + 2], p0[r0 + 3]); pw.z = pk2(p0[r0 + 4], p0[r0 + 5]); pw.w = pk2(p0[r0 + 6], p0[r0 + 7]); }
;                 else { const int r0 = 8 * (j & 1); pw.x = pk2(p1[r0], p1[r0 + 1]); pw.y = pk2(p1[r0 + 2], p1[r0 + 3]); pw.z = pk2(p1[r0 + 4], p1[r0 + 5]); pw.w = pk2(p1[r0 + 6], p1[r0 + 7]); }
;                 const bf16x8 pa = __builtin_bit_cast(bf16x8, pw);
;                 { const s16x4 l4 = *(const LAS s16x4*)(vb + j * 32), hh = *(const LAS s16x4*)(vb + j * 32 + 16);
;                   const bf16x8 vf = {l4[0], l4[1], l4[2], l4[3], hh[0], hh[1], hh[2], hh[3]}; o0 = MFMA32(pa, vf, o0); }
;                 { const s16x4 l4 = *(const LAS s16x4*)(vb + 32 * VP + j * 32), hh = *(const LAS s16x4*)(vb + 32 * VP + j * 32 + 16);
;                   const bf16x8 vf = {l4[0], l4[1], l4[2], l4[3], hh[0], hh[1], hh[2], hh[3]}; o1 = MFMA32(pa, vf, o1); }
;             }
;             done = __all(carry > SB_DONE);
	s_nop 0
	v_permlane32_swap_b32_e32 v144, v148
	v_cndmask_b32_e64 v149, v144, v148, s[40:41]
	v_cndmask_b32_e64 v148, v172, v173, s[40:41]
	v_pk_add_f32 v[146:147], v[146:147], v[142:143]
	v_pk_add_f32 v[172:173], v[140:141], v[148:149]
	v_add_f32_e32 v142, v195, v146
	v_cndmask_b32_e64 v144, 0, v148, s[40:41]
	v_pk_add_f32 v[172:173], v[172:173], v[146:147]
	v_add_f32_e32 v170, v144, v142
	v_add_f32_e32 v144, v195, v172
	v_cndmask_b32_e64 v142, 0, v167, s[40:41]
	v_add_f32_e32 v146, v142, v144
	v_add_f32_e32 v142, v169, v144
	v_cndmask_b32_e64 v148, 0, v171, s[40:41]
	v_add_f32_e32 v148, v148, v142
	v_add_f32_e32 v14, v14, v170
	v_sub_f32_e32 v14, v65, v14
	v_add_f32_e32 v65, v165, v148
	v_sub_f32_e32 v56, v56, v65
	v_add_f32_e32 v65, v164, v166
	v_add_f32_e32 v12, v12, v170
	v_sub_f32_e32 v65, v72, v65
	v_sub_f32_e32 v12, v66, v12
	v_exp_f32_e32 v56, v56
	v_exp_f32_e32 v66, v65
	v_add_f32_e32 v4, v4, v170
	v_sub_f32_e32 v4, v67, v4
	v_cndmask_b32_e64 v65, 0, v56, s[76:77]
	v_cndmask_b32_e64 v56, 0, v66, s[74:75]
	v_add_f32_e32 v66, v163, v148
	v_sub_f32_e32 v57, v57, v66
	v_add_f32_e32 v66, v162, v166
	v_sub_f32_e32 v66, v73, v66
	v_exp_f32_e32 v57, v57
	v_exp_f32_e32 v67, v66
	v_add_f32_e32 v10, v10, v168
	v_sub_f32_e32 v10, v68, v10
	v_cndmask_b32_e64 v66, 0, v57, s[80:81]
	v_cndmask_b32_e64 v57, 0, v67, s[78:79]
	v_add_f32_e32 v67, v151, v148
	v_sub_f32_e32 v58, v58, v67
	v_add_f32_e32 v67, v150, v166
	v_sub_f32_e32 v67, v74, v67
	v_exp_f32_e32 v58, v58
	v_exp_f32_e32 v68, v67
	v_add_f32_e32 v8, v8, v168
	v_sub_f32_e32 v8, v69, v8
	v_cndmask_b32_e64 v67, 0, v58, s[84:85]
	v_cndmask_b32_e64 v58, 0, v68, s[82:83]
	v_add_f32_e32 v68, v153, v148
	v_sub_f32_e32 v59, v59, v68
	v_add_f32_e32 v68, v152, v166
	v_sub_f32_e32 v68, v75, v68
	v_exp_f32_e32 v59, v59
	v_exp_f32_e32 v69, v68
	v_add_f32_e32 v6, v6, v168
	v_sub_f32_e32 v6, v70, v6
	v_cndmask_b32_e64 v68, 0, v59, s[88:89]
	v_cndmask_b32_e64 v59, 0, v69, s[86:87]
	v_add_f32_e32 v69, v155, v146
	v_sub_f32_e32 v60, v60, v69
	v_add_f32_e32 v69, v175, v154
	v_sub_f32_e32 v69, v76, v69
	v_exp_f32_e32 v60, v60
	v_exp_f32_e32 v70, v69
	v_add_f32_e32 v2, v2, v168
	v_sub_f32_e32 v2, v71, v2
	v_cndmask_b32_e64 v69, 0, v60, s[92:93]
	v_cndmask_b32_e64 v60, 0, v70, s[90:91]
	v_add_f32_e32 v70, v157, v146
	v_sub_f32_e32 v61, v61, v70
	v_add_f32_e32 v70, v156, v175
	v_sub_f32_e32 v70, v77, v70
	v_exp_f32_e32 v61, v61
	v_exp_f32_e32 v71, v70
	v_cndmask_b32_e64 v74, 0, v149, s[40:41]
	v_add_f32_e32 v75, v147, v144
	v_add_f32_e32 v74, v74, v75
	v_add_f32_e32 v13, v13, v74
	v_add_f32_e32 v5, v5, v74
	v_cndmask_b32_e64 v70, 0, v61, s[96:97]
	v_cndmask_b32_e64 v61, 0, v71, s[94:95]
	v_add_f32_e32 v71, v159, v146
	v_sub_f32_e32 v13, v50, v13
	v_sub_f32_e32 v5, v51, v5
	v_sub_f32_e32 v62, v62, v71
	v_add_f32_e32 v71, v158, v175
	v_exp_f32_e32 v13, v13
	v_exp_f32_e32 v5, v5
	v_sub_f32_e32 v71, v78, v71
	v_exp_f32_e32 v62, v62
	v_exp_f32_e32 v72, v71
	v_add_f32_e32 v15, v15, v74
	v_cndmask_b32_e64 v13, 0, v13, s[46:47]
	v_cndmask_b32_e64 v5, 0, v5, s[48:49]
	v_sub_f32_e32 v15, v49, v15
	v_cvt_pk_bf16_f32 v49, v13, v5
	v_cndmask_b32_e64 v5, 0, v145, s[40:41]
	v_add_f32_e32 v13, v143, v144
	v_cndmask_b32_e64 v71, 0, v62, s[10:11]
	v_cndmask_b32_e64 v62, 0, v72, s[8:9]
	v_add_f32_e32 v72, v161, v146
	v_add_f32_e32 v5, v5, v13
	v_sub_f32_e32 v63, v63, v72
	v_add_f32_e32 v72, v160, v175
	v_add_f32_e32 v75, v141, v74
	v_add_f32_e32 v11, v11, v5
	v_add_f32_e32 v9, v9, v5
	v_add_f32_e32 v7, v7, v5
	v_add_f32_e32 v3, v3, v5
	v_sub_f32_e32 v72, v79, v72
	v_sub_f32_e32 v48, v48, v75
	v_sub_f32_e32 v11, v52, v11
	v_sub_f32_e32 v9, v53, v9
	v_sub_f32_e32 v7, v54, v7
	v_sub_f32_e32 v3, v55, v3
	v_exp_f32_e32 v63, v63
	v_exp_f32_e32 v73, v72
	v_exp_f32_e32 v48, v48
	v_exp_f32_e32 v15, v15
	v_exp_f32_e32 v11, v11
	v_exp_f32_e32 v9, v9
	v_exp_f32_e32 v7, v7
	v_exp_f32_e32 v3, v3
	v_cndmask_b32_e32 v72, 0, v63, vcc
	v_cndmask_b32_e64 v63, 0, v73, s[12:13]
	v_add_u32_e32 v73, 0, v1
	v_cndmask_b32_e64 v48, 0, v48, s[6:7]
	v_cndmask_b32_e64 v15, 0, v15, s[44:45]
	v_cndmask_b32_e64 v11, 0, v11, s[50:51]
	v_cndmask_b32_e64 v9, 0, v9, s[52:53]
	v_cndmask_b32_e64 v7, 0, v7, s[54:55]
	v_cndmask_b32_e64 v3, 0, v3, s[56:57]
	v_cvt_pk_bf16_f32 v48, v48, v15
	v_cvt_pk_bf16_f32 v50, v11, v9
	v_cvt_pk_bf16_f32 v51, v7, v3
	v_add_u32_e32 v7, 0xf800, v73
	ds_read2_b64 v[52:55], v7 offset0:128 offset1:130
	ds_read2_b64 v[74:77], v7 offset0:132 offset1:134
	v_add_u32_e32 v78, 0x10d00, v73
	v_add_u32_e32 v3, 0x10d10, v73
	s_waitcnt lgkmcnt(1)
	v_mfma_f32_32x32x16_bf16 v[16:31], v[48:51], v[52:55], v[16:31]
	ds_read_b64 v[52:53], v78
	ds_read_b64 v[54:55], v3
	v_add_f32_e32 v140, v140, v170
	v_add_u32_e32 v3, 0x10d20, v73
	v_sub_f32_e32 v64, v64, v140
	v_exp_f32_e32 v64, v64
	v_exp_f32_e32 v14, v14
	s_waitcnt lgkmcnt(0)
	v_mfma_f32_32x32x16_bf16 v[32:47], v[48:51], v[52:55], v[32:47]
	v_cvt_pk_bf16_f32 v48, v65, v66
	v_cvt_pk_bf16_f32 v49, v67, v68
	v_cvt_pk_bf16_f32 v50, v69, v70
	v_cvt_pk_bf16_f32 v51, v71, v72
	ds_read_b64 v[52:53], v3
	v_add_u32_e32 v3, 0x10d30, v73
	v_exp_f32_e32 v12, v12
	v_exp_f32_e32 v4, v4
	v_exp_f32_e32 v10, v10
	v_exp_f32_e32 v8, v8
	v_exp_f32_e32 v6, v6
	v_exp_f32_e32 v2, v2
	ds_read_b64 v[54:55], v3
	v_mfma_f32_32x32x16_bf16 v[16:31], v[48:51], v[74:77], v[16:31]
	v_cndmask_b32_e64 v64, 0, v64, s[58:59]
	v_cndmask_b32_e64 v14, 0, v14, s[60:61]
	v_cndmask_b32_e64 v12, 0, v12, s[62:63]
	v_cndmask_b32_e64 v4, 0, v4, s[64:65]
	v_cndmask_b32_e64 v10, 0, v10, s[66:67]
	v_cndmask_b32_e64 v8, 0, v8, s[68:69]
	v_cndmask_b32_e64 v6, 0, v6, s[70:71]
	v_cndmask_b32_e64 v2, 0, v2, s[72:73]
	s_waitcnt lgkmcnt(0)
	v_mfma_f32_32x32x16_bf16 v[32:47], v[48:51], v[52:55], v[32:47]
	v_cvt_pk_bf16_f32 v48, v64, v14
	v_cvt_pk_bf16_f32 v49, v12, v4
	v_cvt_pk_bf16_f32 v50, v10, v8
	v_cvt_pk_bf16_f32 v51, v6, v2
	ds_read2_b64 v[2:5], v7 offset0:136 offset1:138
	ds_read2_b64 v[6:9], v7 offset0:140 offset1:142
	v_add_f32_e32 v142, v172, v173
	s_waitcnt lgkmcnt(1)
	v_mfma_f32_32x32x16_bf16 v[16:31], v[48:51], v[2:5], v[16:31]
	v_add_u32_e32 v2, 0x10d40, v73
	v_add_u32_e32 v4, 0x10d50, v73
	ds_read_b64 v[2:3], v2
	ds_read_b64 v[4:5], v4
	v_add_f32_e32 v195, v195, v142
	v_cmp_lt_f32_e32 vcc, s5, v195
	s_cmp_eq_u64 vcc, exec
	s_waitcnt lgkmcnt(0)
	v_mfma_f32_32x32x16_bf16 v[32:47], v[48:51], v[2:5], v[32:47]
	v_cvt_pk_bf16_f32 v2, v56, v57
	v_cvt_pk_bf16_f32 v3, v58, v59
	v_cvt_pk_bf16_f32 v4, v60, v61
	v_cvt_pk_bf16_f32 v5, v62, v63
	s_cselect_b64 s[6:7], -1, 0
	s_add_i32 s10, s4, -1
	s_cmp_le_u32 s4, s0
	v_mfma_f32_32x32x16_bf16 v[16:31], v[2:5], v[6:9], v[16:31]
	v_add_u32_e32 v6, 0x10d60, v73
	v_add_u32_e32 v8, 0x10d70, v73
	ds_read_b64 v[6:7], v6
	ds_read_b64 v[8:9], v8
	s_cselect_b64 s[4:5], -1, 0
	s_or_b64 s[8:9], s[4:5], s[6:7]
	s_sub_i32 s19, s19, 64
	s_waitcnt lgkmcnt(0)
	v_mfma_f32_32x32x16_bf16 v[32:47], v[2:5], v[6:9], v[32:47]
	v_add_u32_e32 v1, 0xffffde00, v1
	s_andn2_b64 vcc, exec, s[8:9]
	s_cbranch_vccnz .LBB0_489
	s_mov_b64 s[94:95], 0x100
	s_mov_b64 s[96:97], 0x2000
